# prologue: the silu(c) staging loop issues its 16 loads up front instead of 16 dependent load-wait round trips
# baseline (speedup 1.0000x reference)
.LBB0_15:
	s_or_b64 exec, exec, s[2:3]
	s_load_dwordx16 s[64:79], s[0:1], 0x0
	s_load_dwordx16 s[16:31], s[0:1], 0x40
	s_barrier
	s_waitcnt lgkmcnt(0)
	s_mov_b64 s[88:89], s[12:13]
	v_mov_b32_e32 v0, v210
	v_writelane_b32 v252, s16, 2
	s_mov_b32 s14, s56
	s_mov_b64 s[2:3], s[88:89]
	v_writelane_b32 v252, s17, 3
	v_writelane_b32 v252, s18, 4
	v_writelane_b32 v252, s19, 5
	v_writelane_b32 v252, s20, 6
	v_writelane_b32 v252, s21, 7
	v_writelane_b32 v252, s22, 8
	v_writelane_b32 v252, s23, 9
	v_writelane_b32 v252, s24, 10
	v_writelane_b32 v252, s25, 11
	v_writelane_b32 v252, s26, 12
	v_writelane_b32 v252, s27, 13
	v_writelane_b32 v252, s28, 14
	v_writelane_b32 v252, s29, 15
	v_writelane_b32 v252, s30, 16
	v_writelane_b32 v252, s31, 17
	s_mov_b32 s17, s90
	s_movk_i32 s0, 0x2000
	s_nop 0
	v_readfirstlane_b32 s15, v0
	v_cmp_gt_i32_e32 vcc, s0, v0
	s_and_saveexec_b64 s[0:1], vcc
	s_cbranch_execz .LBB0_18
	v_ashrrev_i32_e32 v1, 31, v0
	v_lshl_add_u32 v5, v0, 2, 0
	v_lshl_add_u64 v[2:3], v[0:1], 2, s[66:67]
	s_mov_b64 s[8:9], 0x1000
	global_load_dword v6, v[2:3], off
	global_load_dword v7, v[2:3], off offset:2048
	v_lshl_add_u64 v[2:3], v[2:3], 0, s[8:9]
	global_load_dword v8, v[2:3], off
	global_load_dword v9, v[2:3], off offset:2048
	v_lshl_add_u64 v[2:3], v[2:3], 0, s[8:9]
	global_load_dword v10, v[2:3], off
	global_load_dword v11, v[2:3], off offset:2048
	v_lshl_add_u64 v[2:3], v[2:3], 0, s[8:9]
	global_load_dword v12, v[2:3], off
	global_load_dword v13, v[2:3], off offset:2048
	v_lshl_add_u64 v[2:3], v[2:3], 0, s[8:9]
	global_load_dword v14, v[2:3], off
	global_load_dword v15, v[2:3], off offset:2048
	v_lshl_add_u64 v[2:3], v[2:3], 0, s[8:9]
	global_load_dword v16, v[2:3], off
	global_load_dword v17, v[2:3], off offset:2048
	v_lshl_add_u64 v[2:3], v[2:3], 0, s[8:9]
	global_load_dword v18, v[2:3], off
	global_load_dword v19, v[2:3], off offset:2048
	v_lshl_add_u64 v[2:3], v[2:3], 0, s[8:9]
	global_load_dword v20, v[2:3], off
	global_load_dword v21, v[2:3], off offset:2048
	s_waitcnt vmcnt(15)
	v_mul_f32_e32 v22, 0xbfb8aa3b, v6
	v_exp_f32_e32 v22, v22
	s_nop 0
	v_add_f32_e32 v22, 1.0, v22
	v_rcp_f32_e32 v22, v22
	s_nop 0
	v_mul_f32_e32 v6, v6, v22
	ds_write_b32 v5, v6
	s_waitcnt vmcnt(14)
	v_mul_f32_e32 v22, 0xbfb8aa3b, v7
	v_exp_f32_e32 v22, v22
	s_nop 0
	v_add_f32_e32 v22, 1.0, v22
	v_rcp_f32_e32 v22, v22
	s_nop 0
	v_mul_f32_e32 v7, v7, v22
	ds_write_b32 v5, v7 offset:2048
	s_waitcnt vmcnt(13)
	v_mul_f32_e32 v22, 0xbfb8aa3b, v8
	v_exp_f32_e32 v22, v22
	s_nop 0
	v_add_f32_e32 v22, 1.0, v22
	v_rcp_f32_e32 v22, v22
	s_nop 0
	v_mul_f32_e32 v8, v8, v22
	ds_write_b32 v5, v8 offset:4096
	s_waitcnt vmcnt(12)
	v_mul_f32_e32 v22, 0xbfb8aa3b, v9
	v_exp_f32_e32 v22, v22
	s_nop 0
	v_add_f32_e32 v22, 1.0, v22
	v_rcp_f32_e32 v22, v22
	s_nop 0
	v_mul_f32_e32 v9, v9, v22
	ds_write_b32 v5, v9 offset:6144
	s_waitcnt vmcnt(11)
	v_mul_f32_e32 v22, 0xbfb8aa3b, v10
	v_exp_f32_e32 v22, v22
	s_nop 0
	v_add_f32_e32 v22, 1.0, v22
	v_rcp_f32_e32 v22, v22
	s_nop 0
	v_mul_f32_e32 v10, v10, v22
	ds_write_b32 v5, v10 offset:8192
	s_waitcnt vmcnt(10)
	v_mul_f32_e32 v22, 0xbfb8aa3b, v11
	v_exp_f32_e32 v22, v22
	s_nop 0
	v_add_f32_e32 v22, 1.0, v22
	v_rcp_f32_e32 v22, v22
	s_nop 0
	v_mul_f32_e32 v11, v11, v22
	ds_write_b32 v5, v11 offset:10240
	s_waitcnt vmcnt(9)
	v_mul_f32_e32 v22, 0xbfb8aa3b, v12
	v_exp_f32_e32 v22, v22
	s_nop 0
	v_add_f32_e32 v22, 1.0, v22
	v_rcp_f32_e32 v22, v22
	s_nop 0
	v_mul_f32_e32 v12, v12, v22
	ds_write_b32 v5, v12 offset:12288
	s_waitcnt vmcnt(8)
	v_mul_f32_e32 v22, 0xbfb8aa3b, v13
	v_exp_f32_e32 v22, v22
	s_nop 0
	v_add_f32_e32 v22, 1.0, v22
	v_rcp_f32_e32 v22, v22
	s_nop 0
	v_mul_f32_e32 v13, v13, v22
	ds_write_b32 v5, v13 offset:14336
	s_waitcnt vmcnt(7)
	v_mul_f32_e32 v22, 0xbfb8aa3b, v14
	v_exp_f32_e32 v22, v22
	s_nop 0
	v_add_f32_e32 v22, 1.0, v22
	v_rcp_f32_e32 v22, v22
	s_nop 0
	v_mul_f32_e32 v14, v14, v22
	ds_write_b32 v5, v14 offset:16384
	s_waitcnt vmcnt(6)
	v_mul_f32_e32 v22, 0xbfb8aa3b, v15
	v_exp_f32_e32 v22, v22
	s_nop 0
	v_add_f32_e32 v22, 1.0, v22
	v_rcp_f32_e32 v22, v22
	s_nop 0
	v_mul_f32_e32 v15, v15, v22
	ds_write_b32 v5, v15 offset:18432
	s_waitcnt vmcnt(5)
	v_mul_f32_e32 v22, 0xbfb8aa3b, v16
	v_exp_f32_e32 v22, v22
	s_nop 0
	v_add_f32_e32 v22, 1.0, v22
	v_rcp_f32_e32 v22, v22
	s_nop 0
	v_mul_f32_e32 v16, v16, v22
	ds_write_b32 v5, v16 offset:20480
	s_waitcnt vmcnt(4)
	v_mul_f32_e32 v22, 0xbfb8aa3b, v17
	v_exp_f32_e32 v22, v22
	s_nop 0
	v_add_f32_e32 v22, 1.0, v22
	v_rcp_f32_e32 v22, v22
	s_nop 0
	v_mul_f32_e32 v17, v17, v22
	ds_write_b32 v5, v17 offset:22528
	s_waitcnt vmcnt(3)
	v_mul_f32_e32 v22, 0xbfb8aa3b, v18
	v_exp_f32_e32 v22, v22
	s_nop 0
	v_add_f32_e32 v22, 1.0, v22
	v_rcp_f32_e32 v22, v22
	s_nop 0
	v_mul_f32_e32 v18, v18, v22
	ds_write_b32 v5, v18 offset:24576
	s_waitcnt vmcnt(2)
	v_mul_f32_e32 v22, 0xbfb8aa3b, v19
	v_exp_f32_e32 v22, v22
	s_nop 0
	v_add_f32_e32 v22, 1.0, v22
	v_rcp_f32_e32 v22, v22
	s_nop 0
	v_mul_f32_e32 v19, v19, v22
	ds_write_b32 v5, v19 offset:26624
	s_waitcnt vmcnt(1)
	v_mul_f32_e32 v22, 0xbfb8aa3b, v20
	v_exp_f32_e32 v22, v22
	s_nop 0
	v_add_f32_e32 v22, 1.0, v22
	v_rcp_f32_e32 v22, v22
	s_nop 0
	v_mul_f32_e32 v20, v20, v22
	ds_write_b32 v5, v20 offset:28672
	s_waitcnt vmcnt(0)
	v_mul_f32_e32 v22, 0xbfb8aa3b, v21
	v_exp_f32_e32 v22, v22
	s_nop 0
	v_add_f32_e32 v22, 1.0, v22
	v_rcp_f32_e32 v22, v22
	s_nop 0
	v_mul_f32_e32 v21, v21, v22
	ds_write_b32 v5, v21 offset:30720
